# k09 flat barrier + removed nt hint from P2/P9 GEMM output stores (outputs stay cached for the consumer phase)
# speedup vs baseline: 1.0052x; 1.0052x over previous
.LBB0_204:
	s_lshl_b32 s11, s18, 8
	v_mbcnt_lo_u32_b32 v144, -1, 0
	v_mbcnt_hi_u32_b32 v144, -1, v144
	s_add_i32 s11, s11, s40
	v_and_or_b32 v152, v144, 15, s11
	s_lshl_b32 s11, s47, 8
	v_ashrrev_i32_e32 v144, 1, v144
	v_and_b32_e32 v144, -8, v144
	s_or_b32 s11, s11, s41
	v_add_u32_e32 v144, s11, v144
	v_ashrrev_i32_e32 v145, 31, v144
	v_lshl_add_u64 v[144:145], v[144:145], 1, s[4:5]
	v_mad_i64_i32 v[150:151], s[20:21], v152, s46, v[144:145]
	v_cvt_pk_bf16_f32 v124, v124, v125
	v_cvt_pk_bf16_f32 v125, v126, v127
	v_cvt_pk_bf16_f32 v126, v120, v121
	v_cvt_pk_bf16_f32 v127, v122, v123
	global_store_dwordx4 v[150:151], v[124:127], off
	v_cvt_pk_bf16_f32 v112, v112, v113
	v_cvt_pk_bf16_f32 v113, v114, v115
	v_cvt_pk_bf16_f32 v114, v104, v105
	v_or_b32_e32 v104, 16, v152
	v_cvt_pk_bf16_f32 v115, v106, v107
	global_store_dwordx4 v[150:151], v[112:115], off offset:256
	s_andn2_b64 vcc, exec, s[2:3]
	s_mov_b64 s[2:3], -1
	v_mad_i64_i32 v[112:113], s[20:21], v104, s46, v[144:145]
	v_cvt_pk_bf16_f32 v104, v116, v117
	v_cvt_pk_bf16_f32 v105, v118, v119
	v_cvt_pk_bf16_f32 v106, v108, v109
	v_cvt_pk_bf16_f32 v107, v110, v111
	global_store_dwordx4 v[112:113], v[104:107], off
	v_cvt_pk_bf16_f32 v96, v96, v97
	v_cvt_pk_bf16_f32 v97, v98, v99
	v_cvt_pk_bf16_f32 v98, v88, v89
	v_or_b32_e32 v88, 32, v152
	v_cvt_pk_bf16_f32 v99, v90, v91
	global_store_dwordx4 v[112:113], v[96:99], off offset:256
	s_nop 1
	v_mad_i64_i32 v[96:97], s[20:21], v88, s46, v[144:145]
	v_cvt_pk_bf16_f32 v88, v100, v101
	v_cvt_pk_bf16_f32 v89, v102, v103
	v_cvt_pk_bf16_f32 v90, v92, v93
	v_cvt_pk_bf16_f32 v91, v94, v95
	global_store_dwordx4 v[96:97], v[88:91], off
	v_cvt_pk_bf16_f32 v80, v80, v81
	v_cvt_pk_bf16_f32 v81, v82, v83
	v_cvt_pk_bf16_f32 v82, v72, v73
	v_or_b32_e32 v72, 48, v152
	v_cvt_pk_bf16_f32 v83, v74, v75
	global_store_dwordx4 v[96:97], v[80:83], off offset:256
	s_nop 1
	v_mad_i64_i32 v[80:81], s[20:21], v72, s46, v[144:145]
	v_cvt_pk_bf16_f32 v72, v84, v85
	v_cvt_pk_bf16_f32 v73, v86, v87
	v_cvt_pk_bf16_f32 v74, v76, v77
	v_cvt_pk_bf16_f32 v75, v78, v79
	global_store_dwordx4 v[80:81], v[72:75], off
	v_cvt_pk_bf16_f32 v68, v68, v69
	v_cvt_pk_bf16_f32 v69, v70, v71
	v_cvt_pk_bf16_f32 v70, v64, v65
	v_add_u32_e32 v64, 0x80, v152
	v_cvt_pk_bf16_f32 v71, v66, v67
	global_store_dwordx4 v[80:81], v[68:71], off offset:256
	v_mad_i64_i32 v[64:65], s[20:21], v64, s46, v[144:145]
	v_cvt_pk_bf16_f32 v60, v60, v61
	v_cvt_pk_bf16_f32 v61, v62, v63
	v_cvt_pk_bf16_f32 v62, v56, v57
	v_cvt_pk_bf16_f32 v63, v58, v59
	global_store_dwordx4 v[64:65], v[60:63], off
	v_cvt_pk_bf16_f32 v48, v48, v49
	v_cvt_pk_bf16_f32 v49, v50, v51
	v_cvt_pk_bf16_f32 v50, v40, v41
	v_add_u32_e32 v40, 0x90, v152
	v_cvt_pk_bf16_f32 v51, v42, v43
	global_store_dwordx4 v[64:65], v[48:51], off offset:256
	s_nop 1
	v_mad_i64_i32 v[48:49], s[20:21], v40, s46, v[144:145]
	v_cvt_pk_bf16_f32 v40, v52, v53
	v_cvt_pk_bf16_f32 v41, v54, v55
	v_cvt_pk_bf16_f32 v42, v44, v45
	v_cvt_pk_bf16_f32 v43, v46, v47
	global_store_dwordx4 v[48:49], v[40:43], off
	v_cvt_pk_bf16_f32 v32, v32, v33
	v_cvt_pk_bf16_f32 v33, v34, v35
	v_cvt_pk_bf16_f32 v34, v24, v25
	v_add_u32_e32 v24, 0xa0, v152
	v_cvt_pk_bf16_f32 v35, v26, v27
	global_store_dwordx4 v[48:49], v[32:35], off offset:256
	s_nop 1
	v_mad_i64_i32 v[32:33], s[20:21], v24, s46, v[144:145]
	v_cvt_pk_bf16_f32 v24, v36, v37
	v_cvt_pk_bf16_f32 v25, v38, v39
	v_cvt_pk_bf16_f32 v26, v28, v29
	v_cvt_pk_bf16_f32 v27, v30, v31
	global_store_dwordx4 v[32:33], v[24:27], off
	v_cvt_pk_bf16_f32 v16, v16, v17
	v_cvt_pk_bf16_f32 v17, v18, v19
	v_cvt_pk_bf16_f32 v18, v8, v9
	v_add_u32_e32 v8, 0xb0, v152
	v_cvt_pk_bf16_f32 v19, v10, v11
	global_store_dwordx4 v[32:33], v[16:19], off offset:256
	s_nop 1
	v_mad_i64_i32 v[16:17], s[20:21], v8, s46, v[144:145]
	v_cvt_pk_bf16_f32 v8, v20, v21
	v_cvt_pk_bf16_f32 v9, v22, v23
	v_cvt_pk_bf16_f32 v10, v12, v13
	v_cvt_pk_bf16_f32 v11, v14, v15
	global_store_dwordx4 v[16:17], v[8:11], off
	v_cvt_pk_bf16_f32 v4, v4, v5
	v_cvt_pk_bf16_f32 v5, v6, v7
	v_cvt_pk_bf16_f32 v6, v0, v1
	v_cvt_pk_bf16_f32 v7, v2, v3
	global_store_dwordx4 v[16:17], v[4:7], off offset:256
	s_cbranch_vccnz .LBB0_197
	s_andn2_b64 vcc, exec, s[0:1]
	s_cbranch_vccnz .LBB0_196
	s_barrier
	s_branch .LBB0_196

.LBB0_780:
	s_lshl_b32 s7, s42, 8
	s_add_i32 s7, s7, s35
	s_lshl_b32 s9, s41, 8
	s_cmp_lt_i32 s41, 18
	v_mbcnt_lo_u32_b32 v155, -1, 0
	v_mbcnt_hi_u32_b32 v155, -1, v155
	s_cselect_b32 s14, 0, 0xffffee00
	v_and_or_b32 v158, v155, 15, s7
	s_cselect_b32 s7, s30, s34
	v_mov_b32_e32 v145, s7
	s_movk_i32 s7, 0x1200
	s_cselect_b32 s15, s29, s31
	s_cselect_b32 s7, s7, 0x800
	v_ashrrev_i32_e32 v155, 1, v155
	s_or_b32 s9, s9, s36
	v_and_b32_e32 v155, -8, v155
	s_add_i32 s9, s9, s14
	v_add_u32_e32 v156, s9, v155
	v_mov_b32_e32 v144, s15
	v_ashrrev_i32_e32 v157, 31, v156
	v_lshl_add_u64 v[144:145], v[156:157], 1, v[144:145]
	v_mad_i64_i32 v[156:157], s[14:15], s7, v158, 0
	v_lshl_add_u64 v[156:157], v[156:157], 1, v[144:145]
	v_cvt_pk_bf16_f32 v124, v124, v125
	v_cvt_pk_bf16_f32 v125, v126, v127
	v_cvt_pk_bf16_f32 v126, v120, v121
	v_cvt_pk_bf16_f32 v127, v122, v123
	global_store_dwordx4 v[156:157], v[124:127], off
	v_cvt_pk_bf16_f32 v112, v112, v113
	v_cvt_pk_bf16_f32 v113, v114, v115
	v_cvt_pk_bf16_f32 v114, v104, v105
	v_or_b32_e32 v104, 16, v158
	v_mad_i64_i32 v[104:105], s[14:15], s7, v104, 0
	v_cvt_pk_bf16_f32 v115, v106, v107
	global_store_dwordx4 v[156:157], v[112:115], off offset:256
	s_andn2_b64 vcc, exec, s[2:3]
	s_mov_b64 s[2:3], -1
	v_lshl_add_u64 v[112:113], v[104:105], 1, v[144:145]
	v_cvt_pk_bf16_f32 v104, v116, v117
	v_cvt_pk_bf16_f32 v105, v118, v119
	v_cvt_pk_bf16_f32 v106, v108, v109
	v_cvt_pk_bf16_f32 v107, v110, v111
	global_store_dwordx4 v[112:113], v[104:107], off
	v_cvt_pk_bf16_f32 v96, v96, v97
	v_cvt_pk_bf16_f32 v97, v98, v99
	v_cvt_pk_bf16_f32 v98, v88, v89
	v_or_b32_e32 v88, 32, v158
	v_mad_i64_i32 v[88:89], s[14:15], s7, v88, 0
	v_cvt_pk_bf16_f32 v99, v90, v91
	global_store_dwordx4 v[112:113], v[96:99], off offset:256
	s_nop 1
	v_lshl_add_u64 v[96:97], v[88:89], 1, v[144:145]
	v_cvt_pk_bf16_f32 v88, v100, v101
	v_cvt_pk_bf16_f32 v89, v102, v103
	v_cvt_pk_bf16_f32 v90, v92, v93
	v_cvt_pk_bf16_f32 v91, v94, v95
	global_store_dwordx4 v[96:97], v[88:91], off
	v_cvt_pk_bf16_f32 v80, v80, v81
	v_cvt_pk_bf16_f32 v81, v82, v83
	v_cvt_pk_bf16_f32 v82, v72, v73
	v_or_b32_e32 v72, 48, v158
	v_mad_i64_i32 v[72:73], s[14:15], s7, v72, 0
	v_cvt_pk_bf16_f32 v83, v74, v75
	global_store_dwordx4 v[96:97], v[80:83], off offset:256
	s_nop 1
	v_lshl_add_u64 v[80:81], v[72:73], 1, v[144:145]
	v_cvt_pk_bf16_f32 v72, v84, v85
	v_cvt_pk_bf16_f32 v73, v86, v87
	v_cvt_pk_bf16_f32 v74, v76, v77
	v_cvt_pk_bf16_f32 v75, v78, v79
	global_store_dwordx4 v[80:81], v[72:75], off
	v_cvt_pk_bf16_f32 v68, v68, v69
	v_cvt_pk_bf16_f32 v69, v70, v71
	v_cvt_pk_bf16_f32 v70, v64, v65
	v_add_u32_e32 v64, 0x80, v158
	v_mad_i64_i32 v[64:65], s[14:15], s7, v64, 0
	v_cvt_pk_bf16_f32 v71, v66, v67
	global_store_dwordx4 v[80:81], v[68:71], off offset:256
	v_lshl_add_u64 v[64:65], v[64:65], 1, v[144:145]
	v_cvt_pk_bf16_f32 v60, v60, v61
	v_cvt_pk_bf16_f32 v61, v62, v63
	v_cvt_pk_bf16_f32 v62, v56, v57
	v_cvt_pk_bf16_f32 v63, v58, v59
	global_store_dwordx4 v[64:65], v[60:63], off
	v_cvt_pk_bf16_f32 v48, v48, v49
	v_cvt_pk_bf16_f32 v49, v50, v51
	v_cvt_pk_bf16_f32 v50, v40, v41
	v_add_u32_e32 v40, 0x90, v158
	v_mad_i64_i32 v[40:41], s[14:15], s7, v40, 0
	v_cvt_pk_bf16_f32 v51, v42, v43
	global_store_dwordx4 v[64:65], v[48:51], off offset:256
	s_nop 1
	v_lshl_add_u64 v[48:49], v[40:41], 1, v[144:145]
	v_cvt_pk_bf16_f32 v40, v52, v53
	v_cvt_pk_bf16_f32 v41, v54, v55
	v_cvt_pk_bf16_f32 v42, v44, v45
	v_cvt_pk_bf16_f32 v43, v46, v47
	global_store_dwordx4 v[48:49], v[40:43], off
	v_cvt_pk_bf16_f32 v32, v32, v33
	v_cvt_pk_bf16_f32 v33, v34, v35
	v_cvt_pk_bf16_f32 v34, v24, v25
	v_add_u32_e32 v24, 0xa0, v158
	v_mad_i64_i32 v[24:25], s[14:15], s7, v24, 0
	v_cvt_pk_bf16_f32 v35, v26, v27
	global_store_dwordx4 v[48:49], v[32:35], off offset:256
	s_nop 1
	v_lshl_add_u64 v[32:33], v[24:25], 1, v[144:145]
	v_cvt_pk_bf16_f32 v24, v36, v37
	v_cvt_pk_bf16_f32 v25, v38, v39
	v_cvt_pk_bf16_f32 v26, v28, v29
	v_cvt_pk_bf16_f32 v27, v30, v31
	global_store_dwordx4 v[32:33], v[24:27], off
	v_cvt_pk_bf16_f32 v16, v16, v17
	v_cvt_pk_bf16_f32 v17, v18, v19
	v_cvt_pk_bf16_f32 v18, v8, v9
	v_add_u32_e32 v8, 0xb0, v158
	v_mad_i64_i32 v[8:9], s[14:15], s7, v8, 0
	v_cvt_pk_bf16_f32 v19, v10, v11
	global_store_dwordx4 v[32:33], v[16:19], off offset:256
	s_nop 1
	v_lshl_add_u64 v[16:17], v[8:9], 1, v[144:145]
	v_cvt_pk_bf16_f32 v8, v20, v21
	v_cvt_pk_bf16_f32 v9, v22, v23
	v_cvt_pk_bf16_f32 v10, v12, v13
	v_cvt_pk_bf16_f32 v11, v14, v15
	global_store_dwordx4 v[16:17], v[8:11], off
	v_cvt_pk_bf16_f32 v4, v4, v5
	v_cvt_pk_bf16_f32 v5, v6, v7
	v_cvt_pk_bf16_f32 v6, v0, v1
	v_cvt_pk_bf16_f32 v7, v2, v3
	global_store_dwordx4 v[16:17], v[4:7], off offset:256
	s_cbranch_vccnz .LBB0_773
	s_andn2_b64 vcc, exec, s[0:1]
	s_cbranch_vccnz .LBB0_772
	s_barrier
	s_branch .LBB0_772
